# diff attention: second pass's Q fragments and first three K/V tiles fetched during the first pass's tail (stage moved off the ring slots)
# baseline (speedup 1.0000x reference)
;   int tidv; asm volatile("v_mbcnt_lo_u32_b32 %0, -1, 0\n\tv_mbcnt_hi_u32_b32 %0, -1, %0":"=v"(tidv)); tidv+=wave_*64;
;   const int tid=tidv,lane=tid&63,r32=lane&31,hi=lane>>5; const int wid=__builtin_amdgcn_readfirstlane(tid>>6);
;   const int q0=qb*QB;
;   const bf16*Qw=Qb+(long)(wid*QBLK)*QP;
;   const unsigned lds0=(unsigned)(uintptr_t)shm;
;   float*wsf=(float*)(shm+LDS_WS)+wid*64;
;   const bf16*ksrc=Kh+(long)lane*KP+wid*8;
;   const bf16*vsrc=Vh+(long)(16*(wid&3)+(lane>>2))*VP+(wid>>2)*32+(lane&3)*8;
;   const unsigned kdst=lds0+LDS_K+wid*1024, vdst=lds0+LDS_V+wid*1024;
;     ...
;   const int vb0=(int)(lds0+LDS_V)+((lane>>4)&1)*32+(lane&3)*8+(4*hi+((lane&15)>>2))*64;
;   const char*Kbase=shm+LDS_K; bf16x8 kf[8];
;   const lds_cptr shm3=(lds_cptr)shm; const lds_cptr kp0=shm3+LDS_K+hi*1024+r32*16; const lds_cptr vp0=shm3+LDS_V+((lane>>4)&1)*32+(lane&3)*8+(4*hi+((lane&15)>>2))*64;
;   const int NT=(q0+QB)/KVBLK;
;   const __attribute__((address_space(3))) unsigned* mimg=(const __attribute__((address_space(3))) unsigned*)(shm3+LDS_OST+wid*MWAVE)+r32;
;   DMA_K(0,0);DMA_V(0,0);DMA_K(1,SLOTB);
;   if constexpr(MASKED){
;     __attribute__((address_space(3))) u32x4* mdst=(__attribute__((address_space(3))) u32x4*)(shm3+LDS_OST+wid*MWAVE)+lane;
;     for(int i=0;i<=qb;++i){ const u32x4 v=((const u32x4*)mwave)[i*64+lane]; mdst[i*64]=v; }
;   }
;   bf16x8 qr[4];
;   #pragma unroll
;   for(int d0=0;d0<4;++d0)qr[d0]=*reinterpret_cast<const bf16x8*>(&Qw[(long)r32*QP+d0*16+hi*8]);
;   float mhat=0.f,l_reg=0.f;f32x16 o[2];o[0]=f32x16{};o[1]=f32x16{};f32x16 negm=f32x16{};asm volatile("":"+v"(negm));
;   const int qrel=wid*QBLK+r32;
;     ...
;   bool resc=false;
;     ...
;   f32x16 pA0,pA1,pB0,pB1;
;   int sl_prev=0,sl_cur=0,sl_next=SLOTB;
;     ...
;   DMA_K(2,2*SLOTB);
;   WAIT_BAR(3);
;   qkt(pA0,pA1,Kbase,qr,negm,r32,hi);asm volatile("s_nop 15\n\ts_nop 7":"+v"(pA0),"+v"(pA1));XMASK(pA0,pA1,0);
; __device__ __forceinline__ void run(Frame& F, int qword) {
;     ...
;             for (int sp = 0; sp < 4; ++sp) {
;                 const int c = sp >> 1, vh = sp & 1;
;                 attn_body::attn_unit<8, false>(qb, QB + rq * 512 + (h * 2 + c) * 64, 512, KB + r0 * 512 + (h * 2 + c) * 64, 512, VB + r0 * 512 + h * 128 + vh * 64, 512,
;                                                ATT + rq * 1024 + 512 + h * 128, 1024, nullptr, shm, F.wave, sp < 2 ? 1 : (sp == 2 ? 2 : 3), vh, lam);
.Lfd_entry:
	v_readlane_b32 s8, v254, 11
	v_mbcnt_lo_u32_b32 v0, -1, 0
	v_mbcnt_hi_u32_b32 v0, -1, v0
	v_and_b32_e32 v2, 31, v0
	v_lshrrev_b32_e32 v3, 5, v0
	s_lshl_b32 s89, s79, 2
	s_add_i32 s89, s89, 4
	s_lshl_b32 s0, s8, 4
	v_lshlrev_b32_e32 v10, 10, v0
	v_add_u32_e32 v10, s0, v10
	s_and_b32 s0, s8, 3
	s_lshl_b32 s0, s0, 14
	s_lshr_b32 s1, s8, 2
	s_lshl_b32 s1, s1, 6
	s_add_i32 s0, s0, s1
	v_lshrrev_b32_e32 v4, 2, v0
	v_lshlrev_b32_e32 v4, 10, v4
	v_and_b32_e32 v5, 3, v0
	v_lshlrev_b32_e32 v5, 4, v5
	v_add3_u32 v11, v4, v5, s0
	v_add_u32_e32 v12, 0x80, v11
	v_lshlrev_b32_e32 v13, 10, v3
	v_lshl_add_u32 v13, v2, 4, v13
	v_bfe_u32 v4, v0, 4, 1
	v_lshlrev_b32_e32 v4, 5, v4
	v_and_b32_e32 v5, 3, v0
	v_lshl_add_u32 v4, v5, 3, v4
	v_bfe_u32 v5, v0, 2, 2
	v_lshl_add_u32 v5, v3, 2, v5
	v_lshl_add_u32 v15, v5, 6, v4
	v_add_u32_e32 v15, 0x8000, v15
	s_lshl_b32 s0, s8, 8
	s_add_i32 s0, s0, 0x22400
	v_lshl_add_u32 v44, v2, 2, s0
	v_lshl_add_u32 v45, v3, 4, s0
	s_lshl_b32 s0, s8, 13
	s_add_i32 s0, s0, 0x12000
	s_cmp_eq_u32 s8, 0
	s_cselect_b32 s0, 0x6000, s0
	s_cmp_eq_u32 s8, 7
	s_mov_b32 s1, 0x20400
	s_cselect_b32 s0, s1, s0
	v_lshl_add_u32 v46, v3, 10, s0
	v_lshl_add_u32 v46, v2, 1, v46
	v_lshl_add_u32 v219, v0, 4, s0
	v_lshrrev_b32_e32 v4, 4, v0
	v_and_b32_e32 v5, 15, v0
	v_lshlrev_b32_e32 v5, 4, v5
	v_lshl_add_u32 v252, v4, 11, v5
	v_lshlrev_b32_e32 v39, 10, v2
	v_lshl_add_u32 v39, v3, 4, v39
	s_lshl_b32 s0, s8, 5
	s_add_i32 s0, s0, s78
	v_add_u32_e32 v33, s0, v2
	v_lshlrev_b32_e32 v4, 2, v3
	v_sub_u32_e32 v33, v33, v4
	s_lshl_b32 s0, s8, 5
	s_add_i32 s0, s0, s26
	s_lshl_b32 s1, s28, 8
	s_add_i32 s1, s1, 0x400
	s_mov_b32 s3, 0
	s_mov_b32 s2, s0
	s_lshl_b64 s[2:3], s[2:3], 11
	s_add_u32 s2, s2, s1
	s_addc_u32 s3, s3, 0
	s_add_u32 s86, s66, s2
	s_addc_u32 s87, s67, s3
	s_lshl_b32 s22, s8, 5
	s_add_i32 s22, s22, s78
	s_add_i32 s23, s22, 31
	s_lshl_b32 s29, s8, 10
	s_mov_b32 s90, 0
.Lfd_pass:
	s_lshl_b32 s0, s28, 1
	s_add_i32 s0, s0, s90
	s_lshl_b32 s0, s0, 7
	s_mov_b32 s3, 0
	s_mov_b32 s2, s30
	s_lshl_b64 s[2:3], s[2:3], 21
	s_add_u32 s80, s62, s2
	s_addc_u32 s81, s63, s3
	s_add_u32 s80, s80, s0
	s_addc_u32 s81, s81, 0
	s_lshl_b32 s1, s28, 8
	s_add_u32 s82, s64, s2
	s_addc_u32 s83, s65, s3
	s_add_u32 s82, s82, s1
	s_addc_u32 s83, s83, 0
	s_lshl_b32 s1, s8, 5
	s_add_i32 s1, s1, s26
	s_mov_b32 s3, 0
	s_mov_b32 s2, s1
	s_lshl_b64 s[2:3], s[2:3], 10
	s_add_u32 s84, s60, s2
	s_addc_u32 s85, s61, s3
	s_add_u32 s84, s84, s0
	s_addc_u32 s85, s85, 0
	s_mov_b64 s[92:93], s[80:81]
	s_cmp_lg_u32 s90, 0
	s_cbranch_scc1 .Lfd_noload
	global_load_dwordx4 v[160:163], v39, s[84:85] offset:0
	global_load_dwordx4 v[164:167], v39, s[84:85] offset:32
	global_load_dwordx4 v[168:171], v39, s[84:85] offset:64
	global_load_dwordx4 v[172:175], v39, s[84:85] offset:96
	s_mov_b32 s94, 0
	s_mov_b32 s95, 0
	s_lshl_b32 s0, s95, 16
	s_add_u32 s44, s92, s0
	s_addc_u32 s45, s93, 0
	s_add_u32 s46, s82, s0
	s_addc_u32 s47, s83, 0
	s_and_b32 s1, s94, 3
	s_lshl_b32 s1, s1, 13
	s_lshl_b32 s2, s1, 1
	s_add_i32 s1, s1, s29
	s_mov_b32 m0, s1
	s_add_i32 s2, s2, s29
	global_load_lds_dwordx4 v10, s[44:45]
	s_add_i32 s2, s2, 0x8000
	s_mov_b32 m0, s2
	s_add_i32 s2, s2, 0x2000
	global_load_lds_dwordx4 v11, s[46:47]
	s_mov_b32 m0, s2
	s_nop 0
	global_load_lds_dwordx4 v12, s[46:47]
	s_mov_b32 s94, 1
	s_mov_b32 s95, 1
	s_lshl_b32 s0, s95, 16
	s_add_u32 s44, s92, s0
	s_addc_u32 s45, s93, 0
	s_add_u32 s46, s82, s0
	s_addc_u32 s47, s83, 0
	s_and_b32 s1, s94, 3
	s_lshl_b32 s1, s1, 13
	s_lshl_b32 s2, s1, 1
	s_add_i32 s1, s1, s29
	s_mov_b32 m0, s1
	s_add_i32 s2, s2, s29
	global_load_lds_dwordx4 v10, s[44:45]
	s_add_i32 s2, s2, 0x8000
	s_mov_b32 m0, s2
	s_add_i32 s2, s2, 0x2000
	global_load_lds_dwordx4 v11, s[46:47]
	s_mov_b32 m0, s2
	s_nop 0
	global_load_lds_dwordx4 v12, s[46:47]
	s_mov_b32 s94, 2
	s_mov_b32 s95, 2
	s_lshl_b32 s0, s95, 16
	s_add_u32 s44, s92, s0
	s_addc_u32 s45, s93, 0
	s_add_u32 s46, s82, s0
	s_addc_u32 s47, s83, 0
	s_and_b32 s1, s94, 3
	s_lshl_b32 s1, s1, 13
	s_lshl_b32 s2, s1, 1
	s_add_i32 s1, s1, s29
	s_mov_b32 m0, s1
	s_add_i32 s2, s2, s29
	global_load_lds_dwordx4 v10, s[44:45]
	s_add_i32 s2, s2, 0x8000
	s_mov_b32 m0, s2
	s_add_i32 s2, s2, 0x2000
	global_load_lds_dwordx4 v11, s[46:47]
	s_mov_b32 m0, s2
	s_nop 0
	global_load_lds_dwordx4 v12, s[46:47]
.Lfd_noload:
	v_mov_b32_e32 v48, 0
	v_mov_b32_e32 v49, 0
	v_mov_b32_e32 v50, 0
	v_mov_b32_e32 v51, 0
	v_mov_b32_e32 v52, 0
	v_mov_b32_e32 v53, 0
	v_mov_b32_e32 v54, 0
	v_mov_b32_e32 v55, 0
	v_mov_b32_e32 v56, 0
	v_mov_b32_e32 v57, 0
	v_mov_b32_e32 v58, 0
	v_mov_b32_e32 v59, 0
	v_mov_b32_e32 v60, 0
	v_mov_b32_e32 v61, 0
	v_mov_b32_e32 v62, 0
	v_mov_b32_e32 v63, 0
	v_mov_b32_e32 v64, 0
	v_mov_b32_e32 v65, 0
	v_mov_b32_e32 v66, 0
	v_mov_b32_e32 v67, 0
	v_mov_b32_e32 v68, 0
	v_mov_b32_e32 v69, 0
	v_mov_b32_e32 v70, 0
	v_mov_b32_e32 v71, 0
	v_mov_b32_e32 v72, 0
	v_mov_b32_e32 v73, 0
	v_mov_b32_e32 v74, 0
	v_mov_b32_e32 v75, 0
	v_mov_b32_e32 v76, 0
	v_mov_b32_e32 v77, 0
	v_mov_b32_e32 v78, 0
	v_mov_b32_e32 v79, 0
	v_mov_b32_e32 v80, 0
	v_mov_b32_e32 v81, 0
	v_mov_b32_e32 v82, 0
	v_mov_b32_e32 v83, 0
	v_mov_b32_e32 v84, 0
	v_mov_b32_e32 v85, 0
	v_mov_b32_e32 v86, 0
	v_mov_b32_e32 v87, 0
	v_mov_b32_e32 v88, 0
	v_mov_b32_e32 v89, 0
	v_mov_b32_e32 v90, 0
	v_mov_b32_e32 v91, 0
	v_mov_b32_e32 v92, 0
	v_mov_b32_e32 v93, 0
	v_mov_b32_e32 v94, 0
	v_mov_b32_e32 v95, 0
	v_mov_b32_e32 v96, 0
	v_mov_b32_e32 v97, 0
	v_mov_b32_e32 v98, 0
	v_mov_b32_e32 v99, 0
	v_mov_b32_e32 v100, 0
	v_mov_b32_e32 v101, 0
	v_mov_b32_e32 v102, 0
	v_mov_b32_e32 v103, 0
	v_mov_b32_e32 v104, 0
	v_mov_b32_e32 v105, 0
	v_mov_b32_e32 v106, 0
	v_mov_b32_e32 v107, 0
	v_mov_b32_e32 v108, 0
	v_mov_b32_e32 v109, 0
	v_mov_b32_e32 v110, 0
	v_mov_b32_e32 v111, 0
	v_mov_b32_e32 v144, 0
	v_mov_b32_e32 v145, 0
	v_mov_b32_e32 v146, 0
	v_mov_b32_e32 v147, 0
	v_mov_b32_e32 v148, 0
	v_mov_b32_e32 v149, 0
	v_mov_b32_e32 v150, 0
	v_mov_b32_e32 v151, 0
	v_mov_b32_e32 v152, 0
	v_mov_b32_e32 v153, 0
	v_mov_b32_e32 v154, 0
	v_mov_b32_e32 v155, 0
	v_mov_b32_e32 v156, 0
	v_mov_b32_e32 v157, 0
	v_mov_b32_e32 v158, 0
	v_mov_b32_e32 v159, 0
	v_mov_b32_e32 v34, 0
	v_mov_b32_e32 v35, 0
	s_mov_b32 s88, 0
	s_cmp_lg_u32 s90, 0
	s_cbranch_scc1 .Lfd_w1
	s_waitcnt vmcnt(6)
	s_branch .Lfd_w2
.Lfd_w1:
	s_waitcnt vmcnt(0)
.Lfd_w2:
	s_barrier
.Lfd_loop:
	s_waitcnt vmcnt(3)
	s_barrier
	s_add_i32 s94, s88, 3
	s_mov_b32 s95, s94
	s_cmp_lt_i32 s94, s89
	s_cbranch_scc1 .Lfd_dmaok
	s_cmp_eq_u32 s90, 0
	s_cbranch_scc0 .Lfd_dmaclamp
	s_sub_i32 s95, s94, s89
	s_add_u32 s92, s80, 0x80
	s_addc_u32 s93, s81, 0
	s_branch .Lfd_dmaok
.Lfd_dmaclamp:
	s_add_i32 s94, s89, -1
	s_mov_b32 s95, s94
.Lfd_dmaok:
	s_lshl_b32 s0, s88, 6
	s_cmp_gt_i32 s0, s23
	s_cbranch_scc0 .Lfd_work
	s_lshl_b32 s0, s95, 16
	s_add_u32 s44, s92, s0
	s_addc_u32 s45, s93, 0
	s_add_u32 s46, s82, s0
	s_addc_u32 s47, s83, 0
	s_and_b32 s1, s94, 3
	s_lshl_b32 s1, s1, 13
	s_lshl_b32 s2, s1, 1
	s_add_i32 s1, s1, s29
	s_mov_b32 m0, s1
	s_add_i32 s2, s2, s29
	global_load_lds_dwordx4 v10, s[44:45]
	s_add_i32 s2, s2, 0x8000
	s_mov_b32 m0, s2
	s_add_i32 s2, s2, 0x2000
	global_load_lds_dwordx4 v11, s[46:47]
	s_mov_b32 m0, s2
	s_nop 0
	global_load_lds_dwordx4 v12, s[46:47]
	s_branch .Lfd_next
.Lfd_work:
	s_and_b32 s0, s88, 3
	s_lshl_b32 s0, s0, 13
	v_add_u32_e32 v14, s0, v13
	ds_read_b128 v[176:179], v14 offset:0
	ds_read_b128 v[180:183], v14 offset:512
	ds_read_b128 v[184:187], v14 offset:2048
	ds_read_b128 v[188:191], v14 offset:2560
	ds_read_b128 v[192:195], v14 offset:4096
	ds_read_b128 v[196:199], v14 offset:4608
	ds_read_b128 v[200:203], v14 offset:6144
	ds_read_b128 v[204:207], v14 offset:6656
	s_and_b32 s0, s88, 3
	s_lshl_b32 s0, s0, 14
	v_add_u32_e32 v32, s0, v15
	s_waitcnt lgkmcnt(6)
	v_mfma_f32_32x32x16_bf16 v[112:127], v[176:179], v[160:163], v[144:159]
	ds_read_b64_tr_b16 v[220:221], v32 offset:8192
	ds_read_b64_tr_b16 v[222:223], v32 offset:8704
	v_mfma_f32_32x32x16_bf16 v[128:143], v[180:183], v[160:163], v[144:159]
	ds_read_b64_tr_b16 v[224:225], v32 offset:9216
	ds_read_b64_tr_b16 v[226:227], v32 offset:9728
	s_waitcnt lgkmcnt(8)
	v_mfma_f32_32x32x16_bf16 v[112:127], v[184:187], v[164:167], v[112:127]
	ds_read_b64_tr_b16 v[228:229], v32 offset:10240
	ds_read_b64_tr_b16 v[230:231], v32 offset:10752
	v_mfma_f32_32x32x16_bf16 v[128:143], v[188:191], v[164:167], v[128:143]
	ds_read_b64_tr_b16 v[232:233], v32 offset:11264
	ds_read_b64_tr_b16 v[234:235], v32 offset:11776
	s_waitcnt lgkmcnt(10)
	v_mfma_f32_32x32x16_bf16 v[112:127], v[192:195], v[168:171], v[112:127]
	ds_read_b64_tr_b16 v[236:237], v32 offset:12288
	ds_read_b64_tr_b16 v[238:239], v32 offset:12800
	v_mfma_f32_32x32x16_bf16 v[128:143], v[196:199], v[168:171], v[128:143]
	ds_read_b64_tr_b16 v[240:241], v32 offset:13312
	ds_read_b64_tr_b16 v[242:243], v32 offset:13824
	s_waitcnt lgkmcnt(12)
	v_mfma_f32_32x32x16_bf16 v[112:127], v[200:203], v[172:175], v[112:127]
	ds_read_b64_tr_b16 v[244:245], v32 offset:14336
	ds_read_b64_tr_b16 v[246:247], v32 offset:14848
	v_mfma_f32_32x32x16_bf16 v[128:143], v[204:207], v[172:175], v[128:143]
	ds_read_b64_tr_b16 v[248:249], v32 offset:15360
	ds_read_b64_tr_b16 v[250:251], v32 offset:15872
	ds_read_b64_tr_b16 v[176:177], v32 offset:0
	ds_read_b64_tr_b16 v[178:179], v32 offset:512
	ds_read_b64_tr_b16 v[180:181], v32 offset:1024
	ds_read_b64_tr_b16 v[182:183], v32 offset:1536
	ds_read_b64_tr_b16 v[184:185], v32 offset:2048
	ds_read_b64_tr_b16 v[186:187], v32 offset:2560
	ds_read_b64_tr_b16 v[188:189], v32 offset:3072
	ds_read_b64_tr_b16 v[190:191], v32 offset:3584
	ds_read_b64_tr_b16 v[192:193], v32 offset:4096
	ds_read_b64_tr_b16 v[194:195], v32 offset:4608
	ds_read_b64_tr_b16 v[196:197], v32 offset:5120
	ds_read_b64_tr_b16 v[198:199], v32 offset:5632
	ds_read_b64_tr_b16 v[200:201], v32 offset:6144
	ds_read_b64_tr_b16 v[202:203], v32 offset:6656
	ds_read_b64_tr_b16 v[204:205], v32 offset:7168
	ds_read_b64_tr_b16 v[206:207], v32 offset:7680
	s_lshl_b32 s0, s95, 16
	s_add_u32 s44, s92, s0
	s_addc_u32 s45, s93, 0
	s_add_u32 s46, s82, s0
	s_addc_u32 s47, s83, 0
	s_and_b32 s1, s94, 3
	s_lshl_b32 s1, s1, 13
	s_lshl_b32 s2, s1, 1
	s_add_i32 s1, s1, s29
	s_mov_b32 m0, s1
	s_add_i32 s2, s2, s29
	global_load_lds_dwordx4 v10, s[44:45]
	s_add_i32 s2, s2, 0x8000
	s_mov_b32 m0, s2
	s_add_i32 s2, s2, 0x2000
	global_load_lds_dwordx4 v11, s[46:47]
	s_mov_b32 m0, s2
	s_nop 0
	global_load_lds_dwordx4 v12, s[46:47]
	s_lshl_b32 s0, s88, 6
	s_add_i32 s1, s0, 63
	s_cmp_le_i32 s1, s22
	s_cbranch_scc1 .Lfd_nomaskA
	v_subrev_u32_e32 v4, s0, v33
	v_cmp_gt_i32_e64 s[36:37], 0, v4
	v_cmp_gt_i32_e64 s[38:39], 1, v4
	v_cmp_gt_i32_e64 s[48:49], 2, v4
	v_cmp_gt_i32_e64 s[50:51], 3, v4
	v_cndmask_b32_e64 v112, v112, v47, s[36:37]
	v_cndmask_b32_e64 v113, v113, v47, s[38:39]
	v_cndmask_b32_e64 v114, v114, v47, s[48:49]
	v_cndmask_b32_e64 v115, v115, v47, s[50:51]
	v_cmp_gt_i32_e64 s[36:37], 8, v4
	v_cmp_gt_i32_e64 s[38:39], 9, v4
	v_cmp_gt_i32_e64 s[48:49], 10, v4
	v_cmp_gt_i32_e64 s[50:51], 11, v4
	v_cndmask_b32_e64 v116, v116, v47, s[36:37]
	v_cndmask_b32_e64 v117, v117, v47, s[38:39]
	v_cndmask_b32_e64 v118, v118, v47, s[48:49]
	v_cndmask_b32_e64 v119, v119, v47, s[50:51]
	v_cmp_gt_i32_e64 s[36:37], 16, v4
	v_cmp_gt_i32_e64 s[38:39], 17, v4
	v_cmp_gt_i32_e64 s[48:49], 18, v4
	v_cmp_gt_i32_e64 s[50:51], 19, v4
	v_cndmask_b32_e64 v120, v120, v47, s[36:37]
	v_cndmask_b32_e64 v121, v121, v47, s[38:39]
	v_cndmask_b32_e64 v122, v122, v47, s[48:49]
	v_cndmask_b32_e64 v123, v123, v47, s[50:51]
	v_cmp_gt_i32_e64 s[36:37], 24, v4
	v_cmp_gt_i32_e64 s[38:39], 25, v4
	v_cmp_gt_i32_e64 s[48:49], 26, v4
	v_cmp_gt_i32_e64 s[50:51], 27, v4
	v_cndmask_b32_e64 v124, v124, v47, s[36:37]
	v_cndmask_b32_e64 v125, v125, v47, s[38:39]
	v_cndmask_b32_e64 v126, v126, v47, s[48:49]
	v_cndmask_b32_e64 v127, v127, v47, s[50:51]
	v_cmp_gt_i32_e64 s[36:37], 32, v4
	v_cmp_gt_i32_e64 s[38:39], 33, v4
	v_cmp_gt_i32_e64 s[48:49], 34, v4
	v_cmp_gt_i32_e64 s[50:51], 35, v4
	v_cndmask_b32_e64 v128, v128, v47, s[36:37]
	v_cndmask_b32_e64 v129, v129, v47, s[38:39]
	v_cndmask_b32_e64 v130, v130, v47, s[48:49]
	v_cndmask_b32_e64 v131, v131, v47, s[50:51]
	v_cmp_gt_i32_e64 s[36:37], 40, v4
	v_cmp_gt_i32_e64 s[38:39], 41, v4
	v_cmp_gt_i32_e64 s[48:49], 42, v4
	v_cmp_gt_i32_e64 s[50:51], 43, v4
	v_cndmask_b32_e64 v132, v132, v47, s[36:37]
	v_cndmask_b32_e64 v133, v133, v47, s[38:39]
	v_cndmask_b32_e64 v134, v134, v47, s[48:49]
	v_cndmask_b32_e64 v135, v135, v47, s[50:51]
	v_cmp_gt_i32_e64 s[36:37], 48, v4
	v_cmp_gt_i32_e64 s[38:39], 49, v4
	v_cmp_gt_i32_e64 s[48:49], 50, v4
	v_cmp_gt_i32_e64 s[50:51], 51, v4
	v_cndmask_b32_e64 v136, v136, v47, s[36:37]
	v_cndmask_b32_e64 v137, v137, v47, s[38:39]
	v_cndmask_b32_e64 v138, v138, v47, s[48:49]
	v_cndmask_b32_e64 v139, v139, v47, s[50:51]
	v_cmp_gt_i32_e64 s[36:37], 56, v4
	v_cmp_gt_i32_e64 s[38:39], 57, v4
	v_cmp_gt_i32_e64 s[48:49], 58, v4
	v_cmp_gt_i32_e64 s[50:51], 59, v4
	v_cndmask_b32_e64 v140, v140, v47, s[36:37]
	v_cndmask_b32_e64 v141, v141, v47, s[38:39]
	v_cndmask_b32_e64 v142, v142, v47, s[48:49]
	v_cndmask_b32_e64 v143, v143, v47, s[50:51]

;     ...
;   bf16x8 qr[4];
;   #pragma unroll
;   for(int d0=0;d0<4;++d0)qr[d0]=*reinterpret_cast<const bf16x8*>(&Qw[(long)r32*QP+d0*16+hi*8]);
.Lfd_next:
	s_add_i32 s88, s88, 1
	s_cmp_lt_i32 s88, s89
	s_cbranch_scc1 .Lfd_loop
	s_cmp_lg_u32 s90, 0
	s_cbranch_scc1 .Lfd_drain1
	s_add_u32 s84, s84, 0x80
	s_addc_u32 s85, s85, 0
	global_load_dwordx4 v[160:163], v39, s[84:85] offset:0
	global_load_dwordx4 v[164:167], v39, s[84:85] offset:32
	global_load_dwordx4 v[168:171], v39, s[84:85] offset:64
	global_load_dwordx4 v[172:175], v39, s[84:85] offset:96
	s_branch .Lfd_drain2

; __device__ __forceinline__ int crow(int r,int hi){return (r&3)+8*(r>>2)+4*hi;}
; __device__ __forceinline__ unsigned cvtpk_s(float lo,float hi){f32x2_t v={lo,hi};bf16x2_t b=__builtin_convertvector(v,bf16x2_t);return __builtin_bit_cast(unsigned,b);}
;     ...
;   {auto rr=__builtin_amdgcn_permlane32_swap(__float_as_uint(l_reg),__float_as_uint(l_reg),false,false);l_reg=__uint_as_float(rr[0])+__uint_as_float(rr[1]);}
;   if(hi==0)wsf[32+r32]=l_reg;asm volatile("s_waitcnt lgkmcnt(0)":::"memory");
;   float rli[16];
;   #pragma unroll
;   for(int r=0;r<16;++r)rli[r]=__builtin_amdgcn_rcpf(wsf[32+crow(r,hi)]);
;   bf16*Ow=Ob+(long)(wid*QBLK)*OP;
;   { bf16*stg=(bf16*)(shm+LDS_OST+wid*MWAVE);
;     bf16*stl=stg+bsel*2048+hi*256+r32;
;     if(emode>=2){
;       #pragma unroll
;       for(int r=0;r<16;++r){
;         #pragma unroll
;         for(int d0=0;d0<2;++d0){ const float old=__uint_as_float((unsigned)stl[cr0(r)*64+d0*32]<<16); stl[cr0(r)*64+d0*32]=(bf16)(cvtpk_s(old-lam*(o[d0][r]*rli[r]),0.f)&0xffffu);} }
;     } else {
;       #pragma unroll
;       for(int r=0;r<16;++r){
;         #pragma unroll
;         for(int d0=0;d0<2;++d0)stl[cr0(r)*64+d0*32]=(bf16)(cvtpk_s(o[d0][r]*rli[r],0.f)&0xffffu);}
.Lfd_drain2:
	s_barrier
	s_nop 7
	s_nop 7
	v_mov_b32_e32 v4, v34
	v_mov_b32_e32 v5, v34
	s_nop 1
	v_permlane32_swap_b32_e32 v4, v5
	v_add_f32_e32 v4, v4, v5
	ds_write_b32 v44, v4 offset:128
	s_waitcnt lgkmcnt(0)
	ds_read_b128 v[112:115], v45 offset:128
	ds_read_b128 v[116:119], v45 offset:160
	ds_read_b128 v[120:123], v45 offset:192
	ds_read_b128 v[124:127], v45 offset:224
	s_waitcnt lgkmcnt(0)
	v_rcp_f32_e32 v112, v112
	v_rcp_f32_e32 v113, v113
	v_rcp_f32_e32 v114, v114
	v_rcp_f32_e32 v115, v115
	v_rcp_f32_e32 v116, v116
	v_rcp_f32_e32 v117, v117
	v_rcp_f32_e32 v118, v118
	v_rcp_f32_e32 v119, v119
	v_rcp_f32_e32 v120, v120
	v_rcp_f32_e32 v121, v121
	v_rcp_f32_e32 v122, v122
	v_rcp_f32_e32 v123, v123
	v_rcp_f32_e32 v124, v124
	v_rcp_f32_e32 v125, v125
	v_rcp_f32_e32 v126, v126
	v_rcp_f32_e32 v127, v127
	s_nop 0
	s_cmp_lg_u32 s90, 0
	s_cbranch_scc1 .Lfd_epi1
	v_mul_f32_e32 v4, v48, v112
	v_cvt_pk_bf16_f32 v4, v4, v4
	ds_write_b16 v46, v4 offset:0
	v_mul_f32_e32 v4, v49, v113
	v_cvt_pk_bf16_f32 v4, v4, v4
	ds_write_b16 v46, v4 offset:256
	v_mul_f32_e32 v4, v50, v114
	v_cvt_pk_bf16_f32 v4, v4, v4
	ds_write_b16 v46, v4 offset:512
	v_mul_f32_e32 v4, v51, v115
	v_cvt_pk_bf16_f32 v4, v4, v4
	ds_write_b16 v46, v4 offset:768
	v_mul_f32_e32 v4, v52, v116
	v_cvt_pk_bf16_f32 v4, v4, v4
	ds_write_b16 v46, v4 offset:2048
	v_mul_f32_e32 v4, v53, v117
	v_cvt_pk_bf16_f32 v4, v4, v4
	ds_write_b16 v46, v4 offset:2304
	v_mul_f32_e32 v4, v54, v118
	v_cvt_pk_bf16_f32 v4, v4, v4
	ds_write_b16 v46, v4 offset:2560
	v_mul_f32_e32 v4, v55, v119
	v_cvt_pk_bf16_f32 v4, v4, v4
	ds_write_b16 v46, v4 offset:2816
	v_mul_f32_e32 v4, v56, v120
	v_cvt_pk_bf16_f32 v4, v4, v4
	ds_write_b16 v46, v4 offset:4096
	v_mul_f32_e32 v4, v57, v121
	v_cvt_pk_bf16_f32 v4, v4, v4
	ds_write_b16 v46, v4 offset:4352
	v_mul_f32_e32 v4, v58, v122
	v_cvt_pk_bf16_f32 v4, v4, v4
	ds_write_b16 v46, v4 offset:4608
	v_mul_f32_e32 v4, v59, v123
	v_cvt_pk_bf16_f32 v4, v4, v4
	ds_write_b16 v46, v4 offset:4864
	v_mul_f32_e32 v4, v60, v124
	v_cvt_pk_bf16_f32 v4, v4, v4
	ds_write_b16 v46, v4 offset:6144
	v_mul_f32_e32 v4, v61, v125
	v_cvt_pk_bf16_f32 v4, v4, v4
	ds_write_b16 v46, v4 offset:6400
	v_mul_f32_e32 v4, v62, v126
	v_cvt_pk_bf16_f32 v4, v4, v4
	ds_write_b16 v46, v4 offset:6656
	v_mul_f32_e32 v4, v63, v127
	v_cvt_pk_bf16_f32 v4, v4, v4
	ds_write_b16 v46, v4 offset:6912
	v_mul_f32_e32 v4, v64, v112
	v_cvt_pk_bf16_f32 v4, v4, v4
	ds_write_b16 v46, v4 offset:64
	v_mul_f32_e32 v4, v65, v113
	v_cvt_pk_bf16_f32 v4, v4, v4
	ds_write_b16 v46, v4 offset:320
	v_mul_f32_e32 v4, v66, v114
	v_cvt_pk_bf16_f32 v4, v4, v4
	ds_write_b16 v46, v4 offset:576
	v_mul_f32_e32 v4, v67, v115
	v_cvt_pk_bf16_f32 v4, v4, v4
	ds_write_b16 v46, v4 offset:832
	v_mul_f32_e32 v4, v68, v116
	v_cvt_pk_bf16_f32 v4, v4, v4
	ds_write_b16 v46, v4 offset:2112
	v_mul_f32_e32 v4, v69, v117
	v_cvt_pk_bf16_f32 v4, v4, v4
	ds_write_b16 v46, v4 offset:2368
	v_mul_f32_e32 v4, v70, v118
	v_cvt_pk_bf16_f32 v4, v4, v4
	ds_write_b16 v46, v4 offset:2624
	v_mul_f32_e32 v4, v71, v119
	v_cvt_pk_bf16_f32 v4, v4, v4
	ds_write_b16 v46, v4 offset:2880
	v_mul_f32_e32 v4, v72, v120
	v_cvt_pk_bf16_f32 v4, v4, v4
	ds_write_b16 v46, v4 offset:4160
	v_mul_f32_e32 v4, v73, v121
	v_cvt_pk_bf16_f32 v4, v4, v4
	ds_write_b16 v46, v4 offset:4416
	v_mul_f32_e32 v4, v74, v122
	v_cvt_pk_bf16_f32 v4, v4, v4
	ds_write_b16 v46, v4 offset:4672
	v_mul_f32_e32 v4, v75, v123
	v_cvt_pk_bf16_f32 v4, v4, v4
	ds_write_b16 v46, v4 offset:4928
	v_mul_f32_e32 v4, v76, v124
	v_cvt_pk_bf16_f32 v4, v4, v4
	ds_write_b16 v46, v4 offset:6208
	v_mul_f32_e32 v4, v77, v125
	v_cvt_pk_bf16_f32 v4, v4, v4
	ds_write_b16 v46, v4 offset:6464
	v_mul_f32_e32 v4, v78, v126
	v_cvt_pk_bf16_f32 v4, v4, v4
	ds_write_b16 v46, v4 offset:6720
	v_mul_f32_e32 v4, v79, v127
	v_cvt_pk_bf16_f32 v4, v4, v4
	ds_write_b16 v46, v4 offset:6976
	v_mul_f32_e32 v4, v80, v112
	v_cvt_pk_bf16_f32 v4, v4, v4
	ds_write_b16 v46, v4 offset:128
	v_mul_f32_e32 v4, v81, v113
	v_cvt_pk_bf16_f32 v4, v4, v4
	ds_write_b16 v46, v4 offset:384
	v_mul_f32_e32 v4, v82, v114
	v_cvt_pk_bf16_f32 v4, v4, v4
	ds_write_b16 v46, v4 offset:640
	v_mul_f32_e32 v4, v83, v115
	v_cvt_pk_bf16_f32 v4, v4, v4
	ds_write_b16 v46, v4 offset:896
	v_mul_f32_e32 v4, v84, v116
	v_cvt_pk_bf16_f32 v4, v4, v4
	ds_write_b16 v46, v4 offset:2176
	v_mul_f32_e32 v4, v85, v117
	v_cvt_pk_bf16_f32 v4, v4, v4
	ds_write_b16 v46, v4 offset:2432
	v_mul_f32_e32 v4, v86, v118
	v_cvt_pk_bf16_f32 v4, v4, v4
	ds_write_b16 v46, v4 offset:2688
	v_mul_f32_e32 v4, v87, v119
	v_cvt_pk_bf16_f32 v4, v4, v4
	ds_write_b16 v46, v4 offset:2944
	v_mul_f32_e32 v4, v88, v120
	v_cvt_pk_bf16_f32 v4, v4, v4
	ds_write_b16 v46, v4 offset:4224
	v_mul_f32_e32 v4, v89, v121
	v_cvt_pk_bf16_f32 v4, v4, v4
	ds_write_b16 v46, v4 offset:4480
	v_mul_f32_e32 v4, v90, v122
	v_cvt_pk_bf16_f32 v4, v4, v4
	ds_write_b16 v46, v4 offset:4736
	v_mul_f32_e32 v4, v91, v123
	v_cvt_pk_bf16_f32 v4, v4, v4
	ds_write_b16 v46, v4 offset:4992
	v_mul_f32_e32 v4, v92, v124
	v_cvt_pk_bf16_f32 v4, v4, v4
	ds_write_b16 v46, v4 offset:6272
	v_mul_f32_e32 v4, v93, v125
	v_cvt_pk_bf16_f32 v4, v4, v4
	ds_write_b16 v46, v4 offset:6528
	v_mul_f32_e32 v4, v94, v126
	v_cvt_pk_bf16_f32 v4, v4, v4
	ds_write_b16 v46, v4 offset:6784
	v_mul_f32_e32 v4, v95, v127
	v_cvt_pk_bf16_f32 v4, v4, v4
	ds_write_b16 v46, v4 offset:7040
	v_mul_f32_e32 v4, v96, v112
	v_cvt_pk_bf16_f32 v4, v4, v4
	ds_write_b16 v46, v4 offset:192
	v_mul_f32_e32 v4, v97, v113
	v_cvt_pk_bf16_f32 v4, v4, v4
	ds_write_b16 v46, v4 offset:448
	v_mul_f32_e32 v4, v98, v114
	v_cvt_pk_bf16_f32 v4, v4, v4
	ds_write_b16 v46, v4 offset:704
	v_mul_f32_e32 v4, v99, v115
	v_cvt_pk_bf16_f32 v4, v4, v4
	ds_write_b16 v46, v4 offset:960
	v_mul_f32_e32 v4, v100, v116
	v_cvt_pk_bf16_f32 v4, v4, v4
	ds_write_b16 v46, v4 offset:2240
	v_mul_f32_e32 v4, v101, v117
	v_cvt_pk_bf16_f32 v4, v4, v4
	ds_write_b16 v46, v4 offset:2496
	v_mul_f32_e32 v4, v102, v118
	v_cvt_pk_bf16_f32 v4, v4, v4
	ds_write_b16 v46, v4 offset:2752
	v_mul_f32_e32 v4, v103, v119
	v_cvt_pk_bf16_f32 v4, v4, v4
	ds_write_b16 v46, v4 offset:3008
	v_mul_f32_e32 v4, v104, v120
	v_cvt_pk_bf16_f32 v4, v4, v4
	ds_write_b16 v46, v4 offset:4288
	v_mul_f32_e32 v4, v105, v121
	v_cvt_pk_bf16_f32 v4, v4, v4
	ds_write_b16 v46, v4 offset:4544
	v_mul_f32_e32 v4, v106, v122
	v_cvt_pk_bf16_f32 v4, v4, v4
	ds_write_b16 v46, v4 offset:4800
	v_mul_f32_e32 v4, v107, v123
	v_cvt_pk_bf16_f32 v4, v4, v4
	ds_write_b16 v46, v4 offset:5056
	v_mul_f32_e32 v4, v108, v124
	v_cvt_pk_bf16_f32 v4, v4, v4
	ds_write_b16 v46, v4 offset:6336
	v_mul_f32_e32 v4, v109, v125
	v_cvt_pk_bf16_f32 v4, v4, v4
	ds_write_b16 v46, v4 offset:6592
	v_mul_f32_e32 v4, v110, v126
	v_cvt_pk_bf16_f32 v4, v4, v4
	ds_write_b16 v46, v4 offset:6848
	v_mul_f32_e32 v4, v111, v127
	v_cvt_pk_bf16_f32 v4, v4, v4
	ds_write_b16 v46, v4 offset:7104
	s_waitcnt lgkmcnt(0)
; #define ATTN_STORE16(p,v) st16_wt((p),(v))
;     ...
;     if(emode==0){
;       #pragma unroll
;       for(int i=0;i<4;++i){const int row=i*8+(lane>>3),ch=lane&7; const u32x4 v=*(const u32x4*)(stg+row*64+ch*8); ATTN_STORE16(Ow+(long)row*OP+ch*8,v);}
	ds_read_b128 v[176:179], v219 offset:0
	ds_read_b128 v[180:183], v219 offset:1024
	ds_read_b128 v[184:187], v219 offset:2048
	ds_read_b128 v[188:191], v219 offset:3072
	ds_read_b128 v[192:195], v219 offset:4096
	ds_read_b128 v[196:199], v219 offset:5120
	ds_read_b128 v[200:203], v219 offset:6144
	ds_read_b128 v[204:207], v219 offset:7168
	s_waitcnt lgkmcnt(0)
	v_mov_b32_e32 v253, v252
	global_store_dwordx4 v253, v[176:179], s[86:87]
	v_add_u32_e32 v253, 0x2000, v253
	global_store_dwordx4 v253, v[180:183], s[86:87]
	v_add_u32_e32 v253, 0x2000, v253
	global_store_dwordx4 v253, v[184:187], s[86:87]
	v_add_u32_e32 v253, 0x2000, v253
	global_store_dwordx4 v253, v[188:191], s[86:87]
	v_add_u32_e32 v253, 0x2000, v253
	global_store_dwordx4 v253, v[192:195], s[86:87]
	v_add_u32_e32 v253, 0x2000, v253
	global_store_dwordx4 v253, v[196:199], s[86:87]
	v_add_u32_e32 v253, 0x2000, v253
	global_store_dwordx4 v253, v[200:203], s[86:87]
	v_add_u32_e32 v253, 0x2000, v253
	global_store_dwordx4 v253, v[204:207], s[86:87]
	s_waitcnt vmcnt(0)
	s_barrier
	s_mov_b32 s90, 1
	s_branch .Lfd_pass
